# baseline (speedup 1.0000x reference)
.Lxn_nopf:
	v_pk_mul_f32 v[30:31], v[16:17], v[16:17]
	v_pk_mul_f32 v[32:33], v[14:15], v[14:15]
	v_pk_mul_f32 v[34:35], v[20:21], v[20:21]
	v_pk_mul_f32 v[36:37], v[18:19], v[18:19]
	v_pk_mov_b32 v[44:45], v[32:33], v[30:31] op_sel:[1,0]
	v_mov_b32_e32 v33, v31
	v_pk_mov_b32 v[30:31], v[36:37], v[34:35] op_sel:[1,0]
	v_mov_b32_e32 v37, v35
	v_mul_f32_e32 v41, v27, v27
	v_mul_f32_e32 v38, v23, v23
	v_mul_f32_e32 v40, v25, v25
	v_pk_add_f32 v[32:33], v[44:45], v[32:33]
	v_pk_add_f32 v[30:31], v[30:31], v[36:37]
	v_mul_f32_e32 v13, v26, v26
	v_mul_f32_e32 v46, v28, v28
	v_mul_f32_e32 v47, v29, v29
	v_pk_fma_f32 v[34:35], v[22:23], v[22:23], v[38:39] op_sel_hi:[1,1,0]
	v_pk_fma_f32 v[38:39], v[24:25], v[24:25], v[40:41] op_sel_hi:[1,1,0]
	v_pk_add_f32 v[32:33], v[32:33], v[32:33] op_sel:[0,1] op_sel_hi:[1,0]
	v_pk_add_f32 v[30:31], v[30:31], v[30:31] op_sel:[0,1] op_sel_hi:[1,0]
	v_mov_b32_e32 v35, v46
	v_mov_b32_e32 v39, v47
	v_mov_b32_e32 v33, v13
	v_mov_b32_e32 v31, v41
	v_pk_add_f32 v[34:35], v[34:35], v[38:39]
	v_pk_add_f32 v[30:31], v[32:33], v[30:31]
	s_nop 0
	v_pk_add_f32 v[30:31], v[30:31], v[34:35]
	s_nop 0
	v_add_f32_e32 v13, v30, v31
	ds_bpermute_b32 v30, v6, v13
	s_waitcnt lgkmcnt(0)
	v_add_f32_e32 v13, v13, v30
	ds_bpermute_b32 v30, v7, v13
	s_waitcnt lgkmcnt(0)
	v_add_f32_e32 v13, v13, v30
	ds_bpermute_b32 v30, v8, v13
	s_waitcnt lgkmcnt(0)
	v_add_f32_e32 v13, v13, v30
	ds_bpermute_b32 v30, v9, v13
	s_waitcnt lgkmcnt(0)
	v_add_f32_e32 v13, v13, v30
	ds_bpermute_b32 v30, v10, v13
	s_waitcnt lgkmcnt(0)
	v_add_f32_e32 v13, v13, v30
	ds_bpermute_b32 v30, v11, v13
	s_waitcnt lgkmcnt(0)
	v_add_f32_e32 v13, v13, v30
	v_fmamk_f32 v13, v13, 0x3a800000, v12
	v_mul_f32_e32 v30, 0x4b800000, v13
	v_cmp_gt_f32_e32 vcc, s10, v13
	s_nop 1
	v_cndmask_b32_e32 v13, v13, v30, vcc
	v_rsq_f32_e32 v13, v13
	s_nop 0
	v_mul_f32_e32 v30, 0x45800000, v13
	v_cndmask_b32_e32 v30, v13, v30, vcc
	v_pk_mul_f32 v[14:15], v[30:31], v[14:15] op_sel_hi:[0,1]
	v_pk_mul_f32 v[16:17], v[30:31], v[16:17] op_sel_hi:[0,1]
	v_cvt_pk_bf16_f32 v14, v14, v15
	v_cvt_pk_bf16_f32 v15, v16, v17
	v_pk_mul_f32 v[20:21], v[30:31], v[20:21] op_sel_hi:[0,1]
	v_pk_mul_f32 v[18:19], v[30:31], v[18:19] op_sel_hi:[0,1]
	s_nop 1
	v_mov_b32_dpp v66, v14 quad_perm:[1,0,3,2] row_mask:0xf bank_mask:0xf
	v_mov_b32_dpp v67, v15 quad_perm:[1,0,3,2] row_mask:0xf bank_mask:0xf
	v_mov_b32_e32 v64, v14
	v_mov_b32_e32 v65, v15
	s_mov_b64 s[94:95], exec
	s_mov_b64 exec, s[92:93]
	global_store_dwordx4 v[4:5], v[64:67], off offset:-1024
	s_mov_b64 exec, s[94:95]
	v_cvt_pk_bf16_f32 v14, v18, v19
	v_cvt_pk_bf16_f32 v15, v20, v21
	v_pk_mul_f32 v[24:25], v[30:31], v[24:25] op_sel_hi:[0,1]
	v_pk_mul_f32 v[22:23], v[30:31], v[22:23] op_sel_hi:[0,1]
	s_nop 1
	v_mov_b32_dpp v66, v14 quad_perm:[1,0,3,2] row_mask:0xf bank_mask:0xf
	v_mov_b32_dpp v67, v15 quad_perm:[1,0,3,2] row_mask:0xf bank_mask:0xf
	v_mov_b32_e32 v64, v14
	v_mov_b32_e32 v65, v15
	s_mov_b64 s[94:95], exec
	s_mov_b64 exec, s[92:93]
	global_store_dwordx4 v[4:5], v[64:67], off offset:-512
	s_mov_b64 exec, s[94:95]
	v_cvt_pk_bf16_f32 v14, v22, v23
	v_cvt_pk_bf16_f32 v15, v24, v25
	v_pk_mul_f32 v[28:29], v[30:31], v[28:29] op_sel_hi:[0,1]
	v_pk_mul_f32 v[26:27], v[30:31], v[26:27] op_sel_hi:[0,1]
	s_nop 1
	v_mov_b32_dpp v66, v14 quad_perm:[1,0,3,2] row_mask:0xf bank_mask:0xf
	v_mov_b32_dpp v67, v15 quad_perm:[1,0,3,2] row_mask:0xf bank_mask:0xf
	v_mov_b32_e32 v64, v14
	v_mov_b32_e32 v65, v15
	s_mov_b64 s[94:95], exec
	s_mov_b64 exec, s[92:93]
	global_store_dwordx4 v[4:5], v[64:67], off
	s_mov_b64 exec, s[94:95]
	v_cvt_pk_bf16_f32 v14, v26, v27
	v_cvt_pk_bf16_f32 v15, v28, v29
	s_nop 1
	v_mov_b32_dpp v66, v14 quad_perm:[1,0,3,2] row_mask:0xf bank_mask:0xf
	v_mov_b32_dpp v67, v15 quad_perm:[1,0,3,2] row_mask:0xf bank_mask:0xf
	v_mov_b32_e32 v64, v14
	v_mov_b32_e32 v65, v15
	s_mov_b64 s[94:95], exec
	s_mov_b64 exec, s[92:93]
	global_store_dwordx4 v[4:5], v[64:67], off offset:512
	s_mov_b64 exec, s[94:95]
	v_lshl_add_u64 v[4:5], v[4:5], 0, s[4:5]
	s_cbranch_scc1 .LBB0_109
	s_waitcnt vmcnt(4)
	v_mov_b64_e32 v[14:15], v[48:49]
	v_mov_b64_e32 v[16:17], v[50:51]
	v_mov_b64_e32 v[18:19], v[52:53]
	v_mov_b64_e32 v[20:21], v[54:55]
	v_mov_b64_e32 v[22:23], v[56:57]
	v_mov_b64_e32 v[24:25], v[58:59]
	v_mov_b64_e32 v[26:27], v[60:61]
	v_mov_b64_e32 v[28:29], v[62:63]
	s_branch .LBB0_108

.Lcb_nopf:
	v_mov_b64_e32 v[16:17], v[24:25]
	v_mov_b64_e32 v[18:19], v[26:27]
	v_lshlrev_b32_e32 v20, 16, v16
	v_and_b32_e32 v21, 0xffff0000, v16
	v_lshlrev_b32_e32 v22, 16, v18
	v_and_b32_e32 v23, 0xffff0000, v18
	v_lshlrev_b32_e32 v16, 16, v17
	v_and_b32_e32 v17, 0xffff0000, v17
	v_lshlrev_b32_e32 v18, 16, v19
	v_and_b32_e32 v19, 0xffff0000, v19
	v_pk_fma_f32 v[20:21], v[4:5], v[22:23], v[20:21] neg_lo:[1,0,0] neg_hi:[1,0,0]
	v_pk_fma_f32 v[16:17], v[4:5], v[18:19], v[16:17] neg_lo:[1,0,0] neg_hi:[1,0,0]
	v_mov_b32_e32 v22, v21
	v_mov_b32_e32 v23, v17
	v_mov_b32_e32 v18, v20
	v_mov_b32_e32 v19, v16
	v_pk_mul_f32 v[22:23], v[22:23], v[22:23]
	s_nop 0
	v_pk_fma_f32 v[18:19], v[18:19], v[18:19], v[22:23]
	s_nop 0
	v_add_f32_e32 v18, v18, v19
	ds_bpermute_b32 v19, v10, v18
	s_waitcnt lgkmcnt(0)
	v_add_f32_e32 v18, v18, v19
	ds_bpermute_b32 v19, v11, v18
	s_waitcnt lgkmcnt(0)
	v_add_f32_e32 v18, v18, v19
	ds_bpermute_b32 v19, v12, v18
	s_waitcnt lgkmcnt(0)
	v_add_f32_e32 v18, v18, v19
	ds_bpermute_b32 v19, v13, v18
	s_waitcnt lgkmcnt(0)
	v_add_f32_e32 v18, v18, v19
	ds_bpermute_b32 v19, v149, v18
	s_waitcnt lgkmcnt(0)
	v_add_f32_e32 v18, v18, v19
	v_fmamk_f32 v18, v18, 0x3c000000, v15
	v_mul_f32_e32 v19, 0x4b800000, v18
	v_cmp_gt_f32_e32 vcc, s5, v18
	s_nop 1
	v_cndmask_b32_e32 v18, v18, v19, vcc
	v_rsq_f32_e32 v18, v18
	s_nop 0
	v_mul_f32_e32 v19, 0x45800000, v18
	v_cndmask_b32_e32 v18, v18, v19, vcc
	v_pk_mul_f32 v[20:21], v[20:21], v[18:19] op_sel_hi:[1,0]
	v_pk_mul_f32 v[16:17], v[16:17], v[18:19] op_sel_hi:[1,0]
	v_pk_mul_f32 v[18:19], v[8:9], v[20:21]
	v_pk_mul_f32 v[16:17], v[6:7], v[16:17]
	v_cvt_pk_bf16_f32 v18, v18, v19
	s_nop 0
	v_cvt_pk_bf16_f32 v19, v16, v17
	s_nop 1
	v_mov_b32_dpp v60, v18 quad_perm:[1,0,3,2] row_mask:0xf bank_mask:0xf
	v_mov_b32_dpp v61, v19 quad_perm:[1,0,3,2] row_mask:0xf bank_mask:0xf
	v_mov_b32_e32 v58, v18
	v_mov_b32_e32 v59, v19
	s_mov_b64 s[94:95], exec
	s_mov_b64 exec, s[92:93]
	global_store_dwordx4 v[2:3], v[58:61], off offset:-1024
	s_mov_b64 exec, s[94:95]
	v_mov_b64_e32 v[16:17], v[28:29]
	v_mov_b64_e32 v[18:19], v[30:31]
	v_lshlrev_b32_e32 v20, 16, v16
	v_and_b32_e32 v21, 0xffff0000, v16
	v_lshlrev_b32_e32 v22, 16, v18
	v_and_b32_e32 v23, 0xffff0000, v18
	v_lshlrev_b32_e32 v16, 16, v17
	v_and_b32_e32 v17, 0xffff0000, v17
	v_lshlrev_b32_e32 v18, 16, v19
	v_and_b32_e32 v19, 0xffff0000, v19
	v_pk_fma_f32 v[20:21], v[4:5], v[22:23], v[20:21] neg_lo:[1,0,0] neg_hi:[1,0,0]
	v_pk_fma_f32 v[16:17], v[4:5], v[18:19], v[16:17] neg_lo:[1,0,0] neg_hi:[1,0,0]
	v_mov_b32_e32 v22, v21
	v_mov_b32_e32 v23, v17
	v_mov_b32_e32 v18, v20
	v_mov_b32_e32 v19, v16
	v_pk_mul_f32 v[22:23], v[22:23], v[22:23]
	s_nop 0
	v_pk_fma_f32 v[18:19], v[18:19], v[18:19], v[22:23]
	s_nop 0
	v_add_f32_e32 v18, v18, v19
	ds_bpermute_b32 v19, v10, v18
	s_waitcnt lgkmcnt(0)
	v_add_f32_e32 v18, v18, v19
	ds_bpermute_b32 v19, v11, v18
	s_waitcnt lgkmcnt(0)
	v_add_f32_e32 v18, v18, v19
	ds_bpermute_b32 v19, v12, v18
	s_waitcnt lgkmcnt(0)
	v_add_f32_e32 v18, v18, v19
	ds_bpermute_b32 v19, v13, v18
	s_waitcnt lgkmcnt(0)
	v_add_f32_e32 v18, v18, v19
	ds_bpermute_b32 v19, v149, v18
	s_waitcnt lgkmcnt(0)
	v_add_f32_e32 v18, v18, v19
	v_fmamk_f32 v18, v18, 0x3c000000, v15
	v_mul_f32_e32 v19, 0x4b800000, v18
	v_cmp_gt_f32_e32 vcc, s5, v18
	s_nop 1
	v_cndmask_b32_e32 v18, v18, v19, vcc
	v_rsq_f32_e32 v18, v18
	s_nop 0
	v_mul_f32_e32 v19, 0x45800000, v18
	v_cndmask_b32_e32 v18, v18, v19, vcc
	v_pk_mul_f32 v[20:21], v[20:21], v[18:19] op_sel_hi:[1,0]
	v_pk_mul_f32 v[16:17], v[16:17], v[18:19] op_sel_hi:[1,0]
	v_pk_mul_f32 v[18:19], v[8:9], v[20:21]
	v_pk_mul_f32 v[16:17], v[6:7], v[16:17]
	v_cvt_pk_bf16_f32 v18, v18, v19
	s_nop 0
	v_cvt_pk_bf16_f32 v19, v16, v17
	s_nop 1
	v_mov_b32_dpp v60, v18 quad_perm:[1,0,3,2] row_mask:0xf bank_mask:0xf
	v_mov_b32_dpp v61, v19 quad_perm:[1,0,3,2] row_mask:0xf bank_mask:0xf
	v_mov_b32_e32 v58, v18
	v_mov_b32_e32 v59, v19
	s_mov_b64 s[94:95], exec
	s_mov_b64 exec, s[92:93]
	global_store_dwordx4 v[2:3], v[58:61], off offset:-512
	s_mov_b64 exec, s[94:95]
	v_mov_b64_e32 v[16:17], v[32:33]
	v_mov_b64_e32 v[18:19], v[34:35]
	v_lshlrev_b32_e32 v20, 16, v16
	v_and_b32_e32 v21, 0xffff0000, v16
	v_lshlrev_b32_e32 v22, 16, v18
	v_and_b32_e32 v23, 0xffff0000, v18
	v_lshlrev_b32_e32 v16, 16, v17
	v_and_b32_e32 v17, 0xffff0000, v17
	v_lshlrev_b32_e32 v18, 16, v19
	v_and_b32_e32 v19, 0xffff0000, v19
	v_pk_fma_f32 v[20:21], v[4:5], v[22:23], v[20:21] neg_lo:[1,0,0] neg_hi:[1,0,0]
	v_pk_fma_f32 v[16:17], v[4:5], v[18:19], v[16:17] neg_lo:[1,0,0] neg_hi:[1,0,0]
	v_mov_b32_e32 v22, v21
	v_mov_b32_e32 v23, v17
	v_mov_b32_e32 v18, v20
	v_mov_b32_e32 v19, v16
	v_pk_mul_f32 v[22:23], v[22:23], v[22:23]
	s_nop 0
	v_pk_fma_f32 v[18:19], v[18:19], v[18:19], v[22:23]
	s_nop 0
	v_add_f32_e32 v18, v18, v19
	ds_bpermute_b32 v19, v10, v18
	s_waitcnt lgkmcnt(0)
	v_add_f32_e32 v18, v18, v19
	ds_bpermute_b32 v19, v11, v18
	s_waitcnt lgkmcnt(0)
	v_add_f32_e32 v18, v18, v19
	ds_bpermute_b32 v19, v12, v18
	s_waitcnt lgkmcnt(0)
	v_add_f32_e32 v18, v18, v19
	ds_bpermute_b32 v19, v13, v18
	s_waitcnt lgkmcnt(0)
	v_add_f32_e32 v18, v18, v19
	ds_bpermute_b32 v19, v149, v18
	s_waitcnt lgkmcnt(0)
	v_add_f32_e32 v18, v18, v19
	v_fmamk_f32 v18, v18, 0x3c000000, v15
	v_mul_f32_e32 v19, 0x4b800000, v18
	v_cmp_gt_f32_e32 vcc, s5, v18
	s_nop 1
	v_cndmask_b32_e32 v18, v18, v19, vcc
	v_rsq_f32_e32 v18, v18
	s_nop 0
	v_mul_f32_e32 v19, 0x45800000, v18
	v_cndmask_b32_e32 v18, v18, v19, vcc
	v_pk_mul_f32 v[20:21], v[20:21], v[18:19] op_sel_hi:[1,0]
	v_pk_mul_f32 v[16:17], v[16:17], v[18:19] op_sel_hi:[1,0]
	v_pk_mul_f32 v[18:19], v[8:9], v[20:21]
	v_pk_mul_f32 v[16:17], v[6:7], v[16:17]
	v_cvt_pk_bf16_f32 v18, v18, v19
	s_nop 0
	v_cvt_pk_bf16_f32 v19, v16, v17
	s_nop 1
	v_mov_b32_dpp v60, v18 quad_perm:[1,0,3,2] row_mask:0xf bank_mask:0xf
	v_mov_b32_dpp v61, v19 quad_perm:[1,0,3,2] row_mask:0xf bank_mask:0xf
	v_mov_b32_e32 v58, v18
	v_mov_b32_e32 v59, v19
	s_mov_b64 s[94:95], exec
	s_mov_b64 exec, s[92:93]
	global_store_dwordx4 v[2:3], v[58:61], off
	s_mov_b64 exec, s[94:95]
	v_mov_b64_e32 v[16:17], v[36:37]
	v_mov_b64_e32 v[18:19], v[38:39]
	v_lshlrev_b32_e32 v20, 16, v16
	v_and_b32_e32 v21, 0xffff0000, v16
	v_lshlrev_b32_e32 v22, 16, v18
	v_and_b32_e32 v23, 0xffff0000, v18
	v_lshlrev_b32_e32 v16, 16, v17
	v_and_b32_e32 v17, 0xffff0000, v17
	v_lshlrev_b32_e32 v18, 16, v19
	v_and_b32_e32 v19, 0xffff0000, v19
	v_pk_fma_f32 v[20:21], v[4:5], v[22:23], v[20:21] neg_lo:[1,0,0] neg_hi:[1,0,0]
	v_pk_fma_f32 v[16:17], v[4:5], v[18:19], v[16:17] neg_lo:[1,0,0] neg_hi:[1,0,0]
	v_mov_b32_e32 v22, v21
	v_mov_b32_e32 v23, v17
	v_mov_b32_e32 v18, v20
	v_mov_b32_e32 v19, v16
	v_pk_mul_f32 v[22:23], v[22:23], v[22:23]
	s_nop 0
	v_pk_fma_f32 v[18:19], v[18:19], v[18:19], v[22:23]
	s_nop 0
	v_add_f32_e32 v18, v18, v19
	ds_bpermute_b32 v19, v10, v18
	s_waitcnt lgkmcnt(0)
	v_add_f32_e32 v18, v18, v19
	ds_bpermute_b32 v19, v11, v18
	s_waitcnt lgkmcnt(0)
	v_add_f32_e32 v18, v18, v19
	ds_bpermute_b32 v19, v12, v18
	s_waitcnt lgkmcnt(0)
	v_add_f32_e32 v18, v18, v19
	ds_bpermute_b32 v19, v13, v18
	s_waitcnt lgkmcnt(0)
	v_add_f32_e32 v18, v18, v19
	ds_bpermute_b32 v19, v149, v18
	s_waitcnt lgkmcnt(0)
	v_add_f32_e32 v18, v18, v19
	v_fmamk_f32 v18, v18, 0x3c000000, v15
	v_mul_f32_e32 v19, 0x4b800000, v18
	v_cmp_gt_f32_e32 vcc, s5, v18
	s_nop 1
	v_cndmask_b32_e32 v18, v18, v19, vcc
	v_rsq_f32_e32 v18, v18
	s_nop 0
	v_mul_f32_e32 v19, 0x45800000, v18
	v_cndmask_b32_e32 v18, v18, v19, vcc
	v_pk_mul_f32 v[20:21], v[20:21], v[18:19] op_sel_hi:[1,0]
	v_pk_mul_f32 v[16:17], v[16:17], v[18:19] op_sel_hi:[1,0]
	v_pk_mul_f32 v[18:19], v[8:9], v[20:21]
	v_pk_mul_f32 v[16:17], v[6:7], v[16:17]
	v_cvt_pk_bf16_f32 v18, v18, v19
	s_nop 0
	v_cvt_pk_bf16_f32 v19, v16, v17
	s_nop 1
	v_mov_b32_dpp v60, v18 quad_perm:[1,0,3,2] row_mask:0xf bank_mask:0xf
	v_mov_b32_dpp v61, v19 quad_perm:[1,0,3,2] row_mask:0xf bank_mask:0xf
	v_mov_b32_e32 v58, v18
	v_mov_b32_e32 v59, v19
	s_mov_b64 s[94:95], exec
	s_mov_b64 exec, s[92:93]
	global_store_dwordx4 v[2:3], v[58:61], off offset:512
	s_mov_b64 exec, s[94:95]
	v_lshl_add_u64 v[2:3], v[2:3], 0, s[8:9]
	s_cbranch_scc0 .Lcb_done
	s_waitcnt vmcnt(4)
	v_mov_b64_e32 v[24:25], v[40:41]
	v_mov_b64_e32 v[26:27], v[42:43]
	v_mov_b64_e32 v[28:29], v[44:45]
	v_mov_b64_e32 v[30:31], v[46:47]
	v_mov_b64_e32 v[32:33], v[48:49]
	v_mov_b64_e32 v[34:35], v[50:51]
	v_mov_b64_e32 v[36:37], v[52:53]
	v_mov_b64_e32 v[38:39], v[54:55]
	s_branch .LBB0_1531
